# attention softmax row-max across lane groups via v_permlane16_swap/v_permlane32_swap instead of two ds_bpermute LDS round trips (on v65)
# baseline (speedup 1.0000x reference)
; __device__ __forceinline__ unsigned pk2(float lo, float hi) { return pg8::cvt_pk_bf16(lo, hi); }
; __device__ __forceinline__ void attn_unit(const bf16* proj, unsigned char* ws, LAS unsigned char* lds, int a) {
;     ...
;             if (kb != n) {
;                 const int sgn = (kb < n) ? 1 : -1, dbase = sgn * (4 * fq - qi);
; #pragma unroll
;                 for (int kt = 0; kt < 8; ++kt)
; #pragma unroll
;                     for (int r = 0; r < 4; ++r) { const int dd = dbase + sgn * (16 * kt + r); st[rt][kt][r] += __builtin_bit_cast(float, (unsigned)(dd >> 31) & 0xF149F2CAu); }
;             }
;             float mx = -1e30f;
; #pragma unroll
;             for (int kt = 0; kt < 8; ++kt)
; #pragma unroll
;                 for (int r = 0; r < 4; ++r) mx = fmaxf(mx, st[rt][kt][r]);
;             mx = fmaxf(mx, __shfl_xor(mx, 16)); mx = fmaxf(mx, __shfl_xor(mx, 32));
;             const float mnew = fmaxf(mrow[rt], mx), alpha = __builtin_amdgcn_exp2f(mrow[rt] - mnew);
;             mrow[rt] = mnew; float ls = lrow[rt] * alpha;
; #pragma unroll
;             for (int dt = 0; dt < 8; ++dt) O[rt][dt] *= alpha;
; #pragma unroll
;             for (int kt = 0; kt < 8; ++kt)
; #pragma unroll
;                 for (int r = 0; r < 4; ++r) { const float p = __builtin_amdgcn_exp2f(st[rt][kt][r] - mnew); st[rt][kt][r] = p; ls += p; }
;             lrow[rt] = ls;
; #pragma unroll
;             for (int tp = 0; tp < 4; ++tp) {
;                 v4u w; w.x = pk2(st[rt][2 * tp][0], st[rt][2 * tp][1]); w.y = pk2(st[rt][2 * tp][2], st[rt][2 * tp][3]);
;                 w.z = pk2(st[rt][2 * tp + 1][0], st[rt][2 * tp + 1][1]); w.w = pk2(st[rt][2 * tp + 1][2], st[rt][2 * tp + 1][3]);
;                 pb[rt][tp] = __builtin_bit_cast(bf16x8, w);
;             }
.LBB0_610:
	v_max3_f32 v207, v92, s67, v93
	v_max3_f32 v207, v207, v94, v95
	v_max3_f32 v207, v207, v100, v101
	v_max3_f32 v207, v207, v102, v103
	v_max3_f32 v207, v207, v104, v105
	v_max3_f32 v207, v207, v106, v107
	v_max3_f32 v207, v207, v108, v109
	v_max3_f32 v207, v207, v110, v111
	v_max3_f32 v207, v207, v144, v145
	v_max3_f32 v207, v207, v146, v147
	v_max3_f32 v207, v207, v148, v149
	v_max3_f32 v207, v207, v150, v151
	v_max3_f32 v207, v207, v152, v153
	v_max3_f32 v207, v207, v154, v155
	v_max3_f32 v207, v207, v156, v157
	v_max3_f32 v207, v207, v158, v159
	v_mov_b32_e32 v238, v207
	s_andn2_b64 vcc, exec, s[56:57]
	s_nop 1
	v_permlane16_swap_b32_e32 v238, v207
	v_max_f32_e32 v207, v207, v238
	v_mov_b32_e32 v238, v207
	s_nop 1
	v_permlane32_swap_b32_e32 v238, v207
	v_max3_f32 v207, v209, v207, v238
	v_sub_f32_e32 v92, v92, v207
	v_exp_f32_e32 v238, v92
	v_sub_f32_e32 v92, v101, v207
	v_exp_f32_e32 v243, v92
	v_sub_f32_e32 v92, v102, v207
	v_exp_f32_e32 v244, v92
	v_sub_f32_e32 v92, v103, v207
	v_exp_f32_e32 v245, v92
	v_sub_f32_e32 v92, v104, v207
	v_exp_f32_e32 v246, v92
	v_sub_f32_e32 v92, v105, v207
	v_exp_f32_e32 v247, v92
	v_sub_f32_e32 v92, v106, v207
	v_exp_f32_e32 v248, v92
	v_sub_f32_e32 v92, v107, v207
	v_exp_f32_e32 v249, v92
	v_sub_f32_e32 v92, v108, v207
	v_exp_f32_e32 v250, v92
	v_sub_f32_e32 v92, v109, v207
	v_exp_f32_e32 v251, v92
	v_sub_f32_e32 v92, v110, v207
	v_exp_f32_e32 v252, v92
	v_sub_f32_e32 v92, v111, v207
	v_exp_f32_e32 v253, v92
	v_sub_f32_e32 v92, v144, v207
	v_exp_f32_e32 v144, v92
	v_sub_f32_e32 v92, v145, v207
	v_exp_f32_e32 v145, v92
	v_sub_f32_e32 v92, v146, v207
	v_exp_f32_e32 v146, v92
	v_sub_f32_e32 v92, v147, v207
	v_exp_f32_e32 v147, v92
	v_sub_f32_e32 v92, v148, v207
	v_exp_f32_e32 v148, v92
	v_sub_f32_e32 v92, v149, v207
	v_exp_f32_e32 v149, v92
	v_sub_f32_e32 v92, v150, v207
	v_exp_f32_e32 v150, v92
	v_sub_f32_e32 v92, v151, v207
	v_exp_f32_e32 v151, v92
	v_sub_f32_e32 v92, v152, v207
	v_exp_f32_e32 v152, v92
	v_sub_f32_e32 v92, v153, v207
	v_exp_f32_e32 v153, v92
	v_sub_f32_e32 v92, v154, v207
	v_exp_f32_e32 v154, v92
	v_sub_f32_e32 v92, v155, v207
	v_exp_f32_e32 v155, v92
	v_sub_f32_e32 v92, v156, v207
	v_exp_f32_e32 v156, v92
	v_sub_f32_e32 v92, v157, v207
	v_exp_f32_e32 v157, v92
	v_sub_f32_e32 v92, v158, v207
	v_sub_f32_e32 v93, v93, v207
	v_sub_f32_e32 v94, v94, v207
	v_sub_f32_e32 v95, v95, v207
	v_sub_f32_e32 v100, v100, v207
	v_exp_f32_e32 v158, v92
	v_sub_f32_e32 v92, v159, v207
	v_exp_f32_e32 v239, v93
	v_exp_f32_e32 v240, v94
	v_exp_f32_e32 v241, v95
	v_exp_f32_e32 v242, v100
	v_exp_f32_e32 v159, v92
	v_cvt_pk_bf16_f32 v108, v238, v239
	v_cvt_pk_bf16_f32 v109, v240, v241
	v_cvt_pk_bf16_f32 v110, v242, v243
	v_cvt_pk_bf16_f32 v111, v244, v245
	v_cvt_pk_bf16_f32 v104, v246, v247
	v_cvt_pk_bf16_f32 v105, v248, v249
	v_cvt_pk_bf16_f32 v106, v250, v251
	v_cvt_pk_bf16_f32 v107, v252, v253
	v_cvt_pk_bf16_f32 v100, v144, v145
	v_cvt_pk_bf16_f32 v101, v146, v147
	v_cvt_pk_bf16_f32 v102, v148, v149
	v_cvt_pk_bf16_f32 v103, v150, v151
	v_cvt_pk_bf16_f32 v92, v152, v153
	v_cvt_pk_bf16_f32 v93, v154, v155
	v_cvt_pk_bf16_f32 v94, v156, v157
	v_cvt_pk_bf16_f32 v95, v158, v159
	s_cbranch_vccnz .LBB0_612
	s_cmp_lt_u32 s70, s69
	s_cbranch_scc0 .Lam_b_next
	v_cmp_gt_i32_e32 vcc, 0, v181
	v_cndmask_b32_e32 v136, v136, v171, vcc
	v_cmp_gt_i32_e32 vcc, -1, v181
	v_cndmask_b32_e32 v137, v137, v171, vcc
	v_cmp_gt_i32_e32 vcc, -2, v181
	v_cndmask_b32_e32 v138, v138, v171, vcc
	v_cmp_gt_i32_e32 vcc, -3, v181
	v_cndmask_b32_e32 v139, v139, v171, vcc
	v_cmp_gt_i32_e32 vcc, -16, v181
	v_cndmask_b32_e32 v132, v132, v171, vcc
	v_cmp_gt_i32_e32 vcc, 0xffffffef, v181
	v_cndmask_b32_e32 v133, v133, v171, vcc
	v_cmp_gt_i32_e32 vcc, 0xffffffee, v181
	v_cndmask_b32_e32 v134, v134, v171, vcc
	v_cmp_gt_i32_e32 vcc, 0xffffffed, v181
	v_cndmask_b32_e32 v135, v135, v171, vcc
	v_cmp_gt_i32_e32 vcc, 0xffffffe0, v181
	v_cndmask_b32_e32 v128, v128, v171, vcc
	v_cmp_gt_i32_e32 vcc, 0xffffffdf, v181
	v_cndmask_b32_e32 v129, v129, v171, vcc
	v_cmp_gt_i32_e32 vcc, 0xffffffde, v181
	v_cndmask_b32_e32 v130, v130, v171, vcc
	v_cmp_gt_i32_e32 vcc, 0xffffffdd, v181
	v_cndmask_b32_e32 v131, v131, v171, vcc
	v_cmp_gt_i32_e32 vcc, 0xffffffd0, v181
	v_cndmask_b32_e32 v124, v124, v171, vcc
	v_cmp_gt_i32_e32 vcc, 0xffffffcf, v181
	v_cndmask_b32_e32 v125, v125, v171, vcc
	v_cmp_gt_i32_e32 vcc, 0xffffffce, v181
	v_cndmask_b32_e32 v126, v126, v171, vcc
	v_cmp_gt_i32_e32 vcc, 0xffffffcd, v181
	v_cndmask_b32_e32 v127, v127, v171, vcc
	v_cmp_gt_i32_e32 vcc, 0xffffffc0, v181
	v_cndmask_b32_e32 v120, v120, v171, vcc
	v_cmp_gt_i32_e32 vcc, 0xffffffbf, v181
	v_cndmask_b32_e32 v121, v121, v171, vcc
	v_cmp_gt_i32_e32 vcc, 0xffffffbe, v181
	v_cndmask_b32_e32 v122, v122, v171, vcc
	v_cmp_gt_i32_e32 vcc, 0xffffffbd, v181
	v_cndmask_b32_e32 v123, v123, v171, vcc
	v_cmp_gt_i32_e32 vcc, 0xffffffb0, v181
	v_cndmask_b32_e32 v116, v116, v171, vcc
	v_cmp_gt_i32_e32 vcc, 0xffffffaf, v181
	v_cndmask_b32_e32 v117, v117, v171, vcc
	v_cmp_gt_i32_e32 vcc, 0xffffffae, v181
	v_cndmask_b32_e32 v118, v118, v171, vcc
	v_cmp_gt_i32_e32 vcc, 0xffffffad, v181
	v_cndmask_b32_e32 v119, v119, v171, vcc
	v_cmp_gt_i32_e32 vcc, 0xffffffa0, v181
	v_cndmask_b32_e32 v112, v112, v171, vcc
	v_cmp_gt_i32_e32 vcc, 0xffffff9f, v181
	v_cndmask_b32_e32 v113, v113, v171, vcc
	v_cmp_gt_i32_e32 vcc, 0xffffff9e, v181
	v_cndmask_b32_e32 v114, v114, v171, vcc
	v_cmp_gt_i32_e32 vcc, 0xffffff9d, v181
	v_cndmask_b32_e32 v115, v115, v171, vcc
	v_cmp_gt_i32_e32 vcc, 16, v181
	v_cndmask_b32_e32 v140, v140, v171, vcc
	v_cmp_gt_i32_e32 vcc, 15, v181
	v_cndmask_b32_e32 v141, v141, v171, vcc
	v_cmp_gt_i32_e32 vcc, 14, v181
	v_cndmask_b32_e32 v142, v142, v171, vcc
	v_cmp_gt_i32_e32 vcc, 13, v181
	v_cndmask_b32_e32 v143, v143, v171, vcc
	s_branch .LBB0_612

; __device__ __forceinline__ unsigned pk2(float lo, float hi) { return pg8::cvt_pk_bf16(lo, hi); }
; __device__ __forceinline__ void attn_unit(const bf16* proj, unsigned char* ws, LAS unsigned char* lds, int a) {
;     ...
;                 for (int r = 0; r < 4; ++r) mx = fmaxf(mx, st[rt][kt][r]);
;             mx = fmaxf(mx, __shfl_xor(mx, 16)); mx = fmaxf(mx, __shfl_xor(mx, 32));
;             const float mnew = fmaxf(mrow[rt], mx), alpha = __builtin_amdgcn_exp2f(mrow[rt] - mnew);
;             mrow[rt] = mnew; float ls = lrow[rt] * alpha;
; #pragma unroll
;             for (int dt = 0; dt < 8; ++dt) O[rt][dt] *= alpha;
; #pragma unroll
;             for (int kt = 0; kt < 8; ++kt)
; #pragma unroll
;                 for (int r = 0; r < 4; ++r) { const float p = __builtin_amdgcn_exp2f(st[rt][kt][r] - mnew); st[rt][kt][r] = p; ls += p; }
;             lrow[rt] = ls;
; #pragma unroll
;             for (int tp = 0; tp < 4; ++tp) {
;                 v4u w; w.x = pk2(st[rt][2 * tp][0], st[rt][2 * tp][1]); w.y = pk2(st[rt][2 * tp][2], st[rt][2 * tp][3]);
;                 w.z = pk2(st[rt][2 * tp + 1][0], st[rt][2 * tp + 1][1]); w.w = pk2(st[rt][2 * tp + 1][2], st[rt][2 * tp + 1][3]);
;                 pb[rt][tp] = __builtin_bit_cast(bf16x8, w);
;             }
.LBB0_612:
	v_sub_f32_e32 v209, v209, v207
	v_exp_f32_e32 v210, v209
	s_add_i32 s70, s70, 1
	s_addk_i32 s51, 0x80
	s_and_b64 vcc, exec, s[54:55]
	v_fmac_f32_e32 v238, v179, v210
	v_add_f32_e32 v179, v239, v238
	v_add_f32_e32 v179, v240, v179
	v_add_f32_e32 v179, v241, v179
	v_add_f32_e32 v179, v242, v179
	v_add_f32_e32 v179, v243, v179
	v_add_f32_e32 v179, v244, v179
	v_add_f32_e32 v179, v245, v179
	v_add_f32_e32 v179, v246, v179
	v_add_f32_e32 v179, v247, v179
	v_add_f32_e32 v179, v248, v179
	v_add_f32_e32 v179, v249, v179
	v_add_f32_e32 v179, v250, v179
	v_add_f32_e32 v179, v251, v179
	v_add_f32_e32 v179, v252, v179
	v_add_f32_e32 v179, v253, v179
	v_add_f32_e32 v144, v144, v179
	v_add_f32_e32 v144, v145, v144
	v_add_f32_e32 v144, v146, v144
	v_add_f32_e32 v144, v147, v144
	v_add_f32_e32 v144, v148, v144
	v_add_f32_e32 v144, v149, v144
	v_add_f32_e32 v144, v150, v144
	v_add_f32_e32 v144, v151, v144
	v_add_f32_e32 v144, v152, v144
	v_add_f32_e32 v144, v153, v144
	v_add_f32_e32 v144, v154, v144
	v_add_f32_e32 v144, v155, v144
	v_add_f32_e32 v144, v156, v144
	v_add_f32_e32 v144, v157, v144
	v_add_f32_e32 v144, v158, v144
	v_add_f32_e32 v179, v159, v144
	v_max3_f32 v144, v140, s67, v141
	v_max3_f32 v144, v144, v142, v143
	v_max3_f32 v144, v144, v136, v137
	v_max3_f32 v144, v144, v138, v139
	v_max3_f32 v144, v144, v132, v133
	v_max3_f32 v144, v144, v134, v135
	v_max3_f32 v144, v144, v128, v129
	v_max3_f32 v144, v144, v130, v131
	v_max3_f32 v144, v144, v124, v125
	v_max3_f32 v144, v144, v126, v127
	v_max3_f32 v144, v144, v120, v121
	v_max3_f32 v144, v144, v122, v123
	v_max3_f32 v144, v144, v116, v117
	v_max3_f32 v144, v144, v118, v119
	v_max3_f32 v144, v144, v112, v113
	v_max3_f32 v144, v144, v114, v115
	v_mov_b32_e32 v145, v144
	v_pk_mul_f32 v[66:67], v[66:67], v[210:211] op_sel_hi:[1,0]
	v_pk_mul_f32 v[64:65], v[64:65], v[210:211] op_sel_hi:[1,0]
	v_pk_mul_f32 v[62:63], v[62:63], v[210:211] op_sel_hi:[1,0]
	v_pk_mul_f32 v[60:61], v[60:61], v[210:211] op_sel_hi:[1,0]
	v_permlane16_swap_b32_e32 v145, v144
	v_max_f32_e32 v144, v144, v145
	v_mov_b32_e32 v145, v144
	v_pk_mul_f32 v[70:71], v[70:71], v[210:211] op_sel_hi:[1,0]
	v_pk_mul_f32 v[68:69], v[68:69], v[210:211] op_sel_hi:[1,0]
	v_pk_mul_f32 v[74:75], v[74:75], v[210:211] op_sel_hi:[1,0]
	v_pk_mul_f32 v[72:73], v[72:73], v[210:211] op_sel_hi:[1,0]
	v_permlane32_swap_b32_e32 v145, v144
	v_max3_f32 v148, v208, v144, v145
	v_sub_f32_e32 v144, v208, v148
	v_exp_f32_e32 v150, v144
	v_sub_f32_e32 v136, v136, v148
	v_exp_f32_e32 v136, v136
	v_sub_f32_e32 v137, v137, v148
	v_pk_mul_f32 v[144:145], v[84:85], v[150:151] op_sel_hi:[1,0]
	v_sub_f32_e32 v84, v140, v148
	v_pk_mul_f32 v[146:147], v[86:87], v[150:151] op_sel_hi:[1,0]
	v_exp_f32_e32 v84, v84
	v_sub_f32_e32 v86, v141, v148
	v_exp_f32_e32 v86, v86
	v_sub_f32_e32 v87, v142, v148
	v_exp_f32_e32 v87, v87
	v_sub_f32_e32 v140, v143, v148
	v_exp_f32_e32 v140, v140
	v_fma_f32 v85, v176, v150, v84
	v_add_f32_e32 v85, v86, v85
	v_exp_f32_e32 v137, v137
	v_sub_f32_e32 v138, v138, v148
	v_add_f32_e32 v85, v87, v85
	v_exp_f32_e32 v138, v138
	v_sub_f32_e32 v139, v139, v148
	v_add_f32_e32 v85, v140, v85
	v_exp_f32_e32 v139, v139
	v_sub_f32_e32 v132, v132, v148
	v_add_f32_e32 v85, v136, v85
	v_exp_f32_e32 v132, v132
	v_sub_f32_e32 v133, v133, v148
	v_add_f32_e32 v85, v137, v85
	v_exp_f32_e32 v133, v133
	v_sub_f32_e32 v134, v134, v148
	v_add_f32_e32 v85, v138, v85
	v_exp_f32_e32 v134, v134
	v_sub_f32_e32 v135, v135, v148
	v_add_f32_e32 v85, v139, v85
	v_exp_f32_e32 v135, v135
	v_sub_f32_e32 v128, v128, v148
	v_add_f32_e32 v85, v132, v85
	v_exp_f32_e32 v128, v128
	v_sub_f32_e32 v129, v129, v148
	v_add_f32_e32 v85, v133, v85
	v_exp_f32_e32 v129, v129
	v_sub_f32_e32 v130, v130, v148
	v_add_f32_e32 v85, v134, v85
	v_exp_f32_e32 v130, v130
	v_sub_f32_e32 v131, v131, v148
	v_add_f32_e32 v85, v135, v85
	v_exp_f32_e32 v131, v131
	v_sub_f32_e32 v124, v124, v148
	v_add_f32_e32 v85, v128, v85
	v_exp_f32_e32 v124, v124
	v_sub_f32_e32 v125, v125, v148
	v_add_f32_e32 v85, v129, v85
	v_exp_f32_e32 v125, v125
	v_sub_f32_e32 v126, v126, v148
	v_add_f32_e32 v85, v130, v85
	v_exp_f32_e32 v126, v126
	v_sub_f32_e32 v127, v127, v148
	v_add_f32_e32 v85, v131, v85
	v_exp_f32_e32 v127, v127
	v_sub_f32_e32 v120, v120, v148
	v_add_f32_e32 v85, v124, v85
	v_exp_f32_e32 v141, v120
	v_sub_f32_e32 v120, v121, v148
	v_add_f32_e32 v85, v125, v85
	v_exp_f32_e32 v142, v120
	v_sub_f32_e32 v120, v122, v148
	v_add_f32_e32 v85, v126, v85
	v_exp_f32_e32 v143, v120
	v_sub_f32_e32 v120, v123, v148
	v_add_f32_e32 v85, v127, v85
	v_exp_f32_e32 v149, v120
	v_sub_f32_e32 v116, v116, v148
	v_pk_mul_f32 v[38:39], v[38:39], v[150:151] op_sel_hi:[1,0]
	v_pk_mul_f32 v[36:37], v[36:37], v[150:151] op_sel_hi:[1,0]
	v_pk_mul_f32 v[34:35], v[34:35], v[150:151] op_sel_hi:[1,0]
	v_pk_mul_f32 v[32:33], v[32:33], v[150:151] op_sel_hi:[1,0]
	v_pk_mul_f32 v[42:43], v[42:43], v[150:151] op_sel_hi:[1,0]
	v_pk_mul_f32 v[40:41], v[40:41], v[150:151] op_sel_hi:[1,0]
	v_pk_mul_f32 v[46:47], v[46:47], v[150:151] op_sel_hi:[1,0]
	v_pk_mul_f32 v[44:45], v[44:45], v[150:151] op_sel_hi:[1,0]
	v_pk_mul_f32 v[50:51], v[50:51], v[150:151] op_sel_hi:[1,0]
	v_pk_mul_f32 v[48:49], v[48:49], v[150:151] op_sel_hi:[1,0]
	v_pk_mul_f32 v[54:55], v[54:55], v[150:151] op_sel_hi:[1,0]
	v_pk_mul_f32 v[52:53], v[52:53], v[150:151] op_sel_hi:[1,0]
	v_pk_mul_f32 v[58:59], v[58:59], v[150:151] op_sel_hi:[1,0]
	v_pk_mul_f32 v[56:57], v[56:57], v[150:151] op_sel_hi:[1,0]
	v_add_f32_e32 v85, v141, v85
	v_exp_f32_e32 v150, v116
	v_sub_f32_e32 v116, v117, v148
	v_add_f32_e32 v85, v142, v85
	v_exp_f32_e32 v151, v116
	v_sub_f32_e32 v116, v118, v148
; #define LAS __attribute__((address_space(3)))
; __device__ __forceinline__ unsigned pk2(float lo, float hi) { return pg8::cvt_pk_bf16(lo, hi); }
; __device__ __forceinline__ void attn_unit(const bf16* proj, unsigned char* ws, LAS unsigned char* lds, int a) {
;     ...
;             for (int kt = 0; kt < 8; ++kt)
; #pragma unroll
;                 for (int r = 0; r < 4; ++r) { const float p = __builtin_amdgcn_exp2f(st[rt][kt][r] - mnew); st[rt][kt][r] = p; ls += p; }
;             lrow[rt] = ls;
; #pragma unroll
;             for (int tp = 0; tp < 4; ++tp) {
;                 v4u w; w.x = pk2(st[rt][2 * tp][0], st[rt][2 * tp][1]); w.y = pk2(st[rt][2 * tp][2], st[rt][2 * tp][3]);
;                 w.z = pk2(st[rt][2 * tp + 1][0], st[rt][2 * tp + 1][1]); w.w = pk2(st[rt][2 * tp + 1][2], st[rt][2 * tp + 1][3]);
;                 pb[rt][tp] = __builtin_bit_cast(bf16x8, w);
;             }
;         }
; #pragma unroll
;         for (int dt = 0; dt < 8; ++dt)
; #pragma unroll
;             for (int tp = 0; tp < 4; ++tp) {
;                 const LAS unsigned char* p0 = VS + (32 * tp + 4 * fq + (fr >> 2)) * V_STRIDE + (16 * dt + 4 * (fr & 3)) * 2;
;                 const bf16x8 vf = tr_frag(p0, p0 + 16 * V_STRIDE);
;                 O[0][dt] = __builtin_amdgcn_mfma_f32_16x16x32_bf16(vf, pb[0][tp], O[0][dt], 0, 0, 0);
;                 O[1][dt] = __builtin_amdgcn_mfma_f32_16x16x32_bf16(vf, pb[1][tp], O[1][dt], 0, 0, 0);
	v_add_f32_e32 v85, v143, v85
	v_exp_f32_e32 v152, v116
	v_sub_f32_e32 v116, v119, v148
	v_add_f32_e32 v85, v149, v85
	v_exp_f32_e32 v153, v116
	v_sub_f32_e32 v112, v112, v148
	v_add_f32_e32 v85, v150, v85
	v_exp_f32_e32 v154, v112
	v_sub_f32_e32 v112, v113, v148
	v_add_f32_e32 v85, v151, v85
	v_exp_f32_e32 v155, v112
	v_sub_f32_e32 v112, v114, v148
	v_add_f32_e32 v85, v152, v85
	v_exp_f32_e32 v156, v112
	v_sub_f32_e32 v112, v115, v148
	v_add_f32_e32 v85, v153, v85
	v_exp_f32_e32 v157, v112
	v_add_f32_e32 v85, v154, v85
	v_add_f32_e32 v85, v155, v85
	v_add_f32_e32 v85, v156, v85
	v_add_f32_e32 v176, v157, v85
	v_cvt_pk_bf16_f32 v120, v84, v86
	v_cvt_pk_bf16_f32 v121, v87, v140
	v_cvt_pk_bf16_f32 v122, v136, v137
	v_cvt_pk_bf16_f32 v123, v138, v139
	v_cvt_pk_bf16_f32 v116, v132, v133
	v_cvt_pk_bf16_f32 v117, v134, v135
	v_cvt_pk_bf16_f32 v118, v128, v129
	v_cvt_pk_bf16_f32 v119, v130, v131
	v_cvt_pk_bf16_f32 v112, v124, v125
	v_cvt_pk_bf16_f32 v113, v126, v127
	v_cvt_pk_bf16_f32 v114, v141, v142
	v_cvt_pk_bf16_f32 v115, v143, v149
	v_cvt_pk_bf16_f32 v84, v150, v151
	v_cvt_pk_bf16_f32 v85, v152, v153
	v_cvt_pk_bf16_f32 v86, v154, v155
	v_cvt_pk_bf16_f32 v87, v156, v157
	ds_read_b64_tr_b16 v[124:125], v202
	ds_read_b64_tr_b16 v[126:127], v202 offset:4608
	ds_read_b64_tr_b16 v[128:129], v202 offset:9216
	ds_read_b64_tr_b16 v[130:131], v202 offset:13824
	ds_read_b64_tr_b16 v[132:133], v202 offset:18432
	ds_read_b64_tr_b16 v[134:135], v202 offset:23040
	v_mul_f32_e64 v78, v78, v210
	v_mul_f32_e64 v79, v79, v210
	v_pk_mul_f32 v[76:77], v[76:77], v[210:211] op_sel_hi:[1,0]
	v_pk_mul_f32 v[82:83], v[82:83], v[210:211] op_sel_hi:[1,0]
	v_pk_mul_f32 v[80:81], v[80:81], v[210:211] op_sel_hi:[1,0]
	v_pk_mul_f32 v[90:91], v[90:91], v[210:211] op_sel_hi:[1,0]
	v_mul_f32_e64 v88, v88, v210
	v_mul_f32_e64 v89, v89, v210
	v_pk_mul_f32 v[98:99], v[98:99], v[210:211] op_sel_hi:[1,0]
	v_pk_mul_f32 v[96:97], v[96:97], v[210:211] op_sel_hi:[1,0]
	ds_read_b64_tr_b16 v[136:137], v202 offset:27648
	ds_read_b64_tr_b16 v[138:139], v202 offset:32256
	s_waitcnt lgkmcnt(6)
	v_mfma_f32_16x16x32_bf16 v[64:67], v[124:127], v[108:111], v[64:67]
	v_mfma_f32_16x16x32_bf16 v[36:39], v[124:127], v[120:123], v[36:39]
	ds_read_b64_tr_b16 v[124:125], v202 offset:32
	ds_read_b64_tr_b16 v[126:127], v202 offset:4640
	s_waitcnt lgkmcnt(6)
	v_mfma_f32_16x16x32_bf16 v[64:67], v[128:131], v[104:107], v[64:67]
	v_mfma_f32_16x16x32_bf16 v[36:39], v[128:131], v[116:119], v[36:39]
	ds_read_b64_tr_b16 v[128:129], v202 offset:9248
	ds_read_b64_tr_b16 v[130:131], v202 offset:13856
	s_waitcnt lgkmcnt(6)
	v_mfma_f32_16x16x32_bf16 v[64:67], v[132:135], v[100:103], v[64:67]
	v_mfma_f32_16x16x32_bf16 v[36:39], v[132:135], v[112:115], v[36:39]
	ds_read_b64_tr_b16 v[132:133], v202 offset:18464
	ds_read_b64_tr_b16 v[134:135], v202 offset:23072
	s_waitcnt lgkmcnt(6)
	v_mfma_f32_16x16x32_bf16 v[64:67], v[136:139], v[92:95], v[64:67]
	v_mfma_f32_16x16x32_bf16 v[36:39], v[136:139], v[84:87], v[36:39]
	ds_read_b64_tr_b16 v[136:137], v202 offset:27680
	ds_read_b64_tr_b16 v[138:139], v202 offset:32288
	s_waitcnt lgkmcnt(6)
	v_mfma_f32_16x16x32_bf16 v[60:63], v[124:127], v[108:111], v[60:63]
	v_mfma_f32_16x16x32_bf16 v[32:35], v[124:127], v[120:123], v[32:35]
	ds_read_b64_tr_b16 v[124:125], v202 offset:64
	ds_read_b64_tr_b16 v[126:127], v202 offset:4672
	s_waitcnt lgkmcnt(6)
	v_mfma_f32_16x16x32_bf16 v[60:63], v[128:131], v[104:107], v[60:63]
	v_mfma_f32_16x16x32_bf16 v[32:35], v[128:131], v[116:119], v[32:35]
	ds_read_b64_tr_b16 v[128:129], v202 offset:9280
	ds_read_b64_tr_b16 v[130:131], v202 offset:13888
	s_waitcnt lgkmcnt(6)
	v_mfma_f32_16x16x32_bf16 v[60:63], v[132:135], v[100:103], v[60:63]
	v_mfma_f32_16x16x32_bf16 v[32:35], v[132:135], v[112:115], v[32:35]
	ds_read_b64_tr_b16 v[132:133], v202 offset:18496
	ds_read_b64_tr_b16 v[134:135], v202 offset:23104
	s_waitcnt lgkmcnt(6)
	v_mfma_f32_16x16x32_bf16 v[60:63], v[136:139], v[92:95], v[60:63]
	v_mfma_f32_16x16x32_bf16 v[32:35], v[136:139], v[84:87], v[32:35]
	ds_read_b64_tr_b16 v[136:137], v202 offset:27712
	ds_read_b64_tr_b16 v[138:139], v202 offset:32320
	s_waitcnt lgkmcnt(6)
	v_mfma_f32_16x16x32_bf16 v[68:71], v[124:127], v[108:111], v[68:71]
	v_mfma_f32_16x16x32_bf16 v[40:43], v[124:127], v[120:123], v[40:43]
	ds_read_b64_tr_b16 v[124:125], v202 offset:96
	ds_read_b64_tr_b16 v[126:127], v202 offset:4704
	s_waitcnt lgkmcnt(6)
	v_mfma_f32_16x16x32_bf16 v[68:71], v[128:131], v[104:107], v[68:71]
	v_mfma_f32_16x16x32_bf16 v[40:43], v[128:131], v[116:119], v[40:43]
	ds_read_b64_tr_b16 v[128:129], v202 offset:9312
	ds_read_b64_tr_b16 v[130:131], v202 offset:13920
	s_waitcnt lgkmcnt(6)
	v_mfma_f32_16x16x32_bf16 v[68:71], v[132:135], v[100:103], v[68:71]
	v_mfma_f32_16x16x32_bf16 v[40:43], v[132:135], v[112:115], v[40:43]
	ds_read_b64_tr_b16 v[132:133], v202 offset:18528
	ds_read_b64_tr_b16 v[134:135], v202 offset:23136
	s_waitcnt lgkmcnt(6)
; #define LAS __attribute__((address_space(3)))
; __device__ __forceinline__ void attn_unit(const bf16* proj, unsigned char* ws, LAS unsigned char* lds, int a) {
;     ...
; #pragma unroll
;         for (int dt = 0; dt < 8; ++dt)
; #pragma unroll
;             for (int tp = 0; tp < 4; ++tp) {
;                 const LAS unsigned char* p0 = VS + (32 * tp + 4 * fq + (fr >> 2)) * V_STRIDE + (16 * dt + 4 * (fr & 3)) * 2;
;                 const bf16x8 vf = tr_frag(p0, p0 + 16 * V_STRIDE);
;                 O[0][dt] = __builtin_amdgcn_mfma_f32_16x16x32_bf16(vf, pb[0][tp], O[0][dt], 0, 0, 0);
;                 O[1][dt] = __builtin_amdgcn_mfma_f32_16x16x32_bf16(vf, pb[1][tp], O[1][dt], 0, 0, 0);
;             }
;     }
	v_mfma_f32_16x16x32_bf16 v[68:71], v[136:139], v[92:95], v[68:71]
	v_mfma_f32_16x16x32_bf16 v[40:43], v[136:139], v[84:87], v[40:43]
	ds_read_b64_tr_b16 v[136:137], v202 offset:27744
	ds_read_b64_tr_b16 v[138:139], v202 offset:32352
	s_waitcnt lgkmcnt(6)
	v_mfma_f32_16x16x32_bf16 v[72:75], v[124:127], v[108:111], v[72:75]
	v_mfma_f32_16x16x32_bf16 v[44:47], v[124:127], v[120:123], v[44:47]
	ds_read_b64_tr_b16 v[124:125], v202 offset:128
	ds_read_b64_tr_b16 v[126:127], v202 offset:4736
	s_waitcnt lgkmcnt(6)
	v_mfma_f32_16x16x32_bf16 v[72:75], v[128:131], v[104:107], v[72:75]
	v_mfma_f32_16x16x32_bf16 v[44:47], v[128:131], v[116:119], v[44:47]
	ds_read_b64_tr_b16 v[128:129], v202 offset:9344
	ds_read_b64_tr_b16 v[130:131], v202 offset:13952
	s_waitcnt lgkmcnt(6)
	v_mfma_f32_16x16x32_bf16 v[72:75], v[132:135], v[100:103], v[72:75]
	v_mfma_f32_16x16x32_bf16 v[44:47], v[132:135], v[112:115], v[44:47]
	ds_read_b64_tr_b16 v[132:133], v202 offset:18560
	ds_read_b64_tr_b16 v[134:135], v202 offset:23168
	s_waitcnt lgkmcnt(6)
	v_mfma_f32_16x16x32_bf16 v[72:75], v[136:139], v[92:95], v[72:75]
	v_mfma_f32_16x16x32_bf16 v[44:47], v[136:139], v[84:87], v[44:47]
	ds_read_b64_tr_b16 v[136:137], v202 offset:27776
	ds_read_b64_tr_b16 v[138:139], v202 offset:32384
	s_waitcnt lgkmcnt(6)
	v_mfma_f32_16x16x32_bf16 v[76:79], v[124:127], v[108:111], v[76:79]
	v_mfma_f32_16x16x32_bf16 v[48:51], v[124:127], v[120:123], v[48:51]
	ds_read_b64_tr_b16 v[124:125], v202 offset:160
	ds_read_b64_tr_b16 v[126:127], v202 offset:4768
	s_waitcnt lgkmcnt(6)
	v_mfma_f32_16x16x32_bf16 v[76:79], v[128:131], v[104:107], v[76:79]
	v_mfma_f32_16x16x32_bf16 v[48:51], v[128:131], v[116:119], v[48:51]
	ds_read_b64_tr_b16 v[128:129], v202 offset:9376
	ds_read_b64_tr_b16 v[130:131], v202 offset:13984
	s_waitcnt lgkmcnt(6)
	v_mfma_f32_16x16x32_bf16 v[76:79], v[132:135], v[100:103], v[76:79]
	v_mfma_f32_16x16x32_bf16 v[48:51], v[132:135], v[112:115], v[48:51]
	ds_read_b64_tr_b16 v[132:133], v202 offset:18592
	ds_read_b64_tr_b16 v[134:135], v202 offset:23200
	s_waitcnt lgkmcnt(6)
	v_mfma_f32_16x16x32_bf16 v[76:79], v[136:139], v[92:95], v[76:79]
	v_mfma_f32_16x16x32_bf16 v[48:51], v[136:139], v[84:87], v[48:51]
	ds_read_b64_tr_b16 v[136:137], v202 offset:27808
	ds_read_b64_tr_b16 v[138:139], v202 offset:32416
	s_waitcnt lgkmcnt(6)
	v_mfma_f32_16x16x32_bf16 v[80:83], v[124:127], v[108:111], v[80:83]
	v_mfma_f32_16x16x32_bf16 v[52:55], v[124:127], v[120:123], v[52:55]
	ds_read_b64_tr_b16 v[124:125], v202 offset:192
	ds_read_b64_tr_b16 v[126:127], v202 offset:4800
	s_waitcnt lgkmcnt(6)
	v_mfma_f32_16x16x32_bf16 v[80:83], v[128:131], v[104:107], v[80:83]
	v_mfma_f32_16x16x32_bf16 v[52:55], v[128:131], v[116:119], v[52:55]
	ds_read_b64_tr_b16 v[128:129], v202 offset:9408
	ds_read_b64_tr_b16 v[130:131], v202 offset:14016
	s_waitcnt lgkmcnt(6)
	v_mfma_f32_16x16x32_bf16 v[80:83], v[132:135], v[100:103], v[80:83]
	v_mfma_f32_16x16x32_bf16 v[52:55], v[132:135], v[112:115], v[52:55]
	ds_read_b64_tr_b16 v[132:133], v202 offset:18624
	ds_read_b64_tr_b16 v[134:135], v202 offset:23232
	s_waitcnt lgkmcnt(6)
	v_mfma_f32_16x16x32_bf16 v[80:83], v[136:139], v[92:95], v[80:83]
	v_mfma_f32_16x16x32_bf16 v[52:55], v[136:139], v[84:87], v[52:55]
	ds_read_b64_tr_b16 v[136:137], v202 offset:27840
	ds_read_b64_tr_b16 v[138:139], v202 offset:32448
	s_waitcnt lgkmcnt(6)
	v_mfma_f32_16x16x32_bf16 v[88:91], v[124:127], v[108:111], v[88:91]
	v_mfma_f32_16x16x32_bf16 v[56:59], v[124:127], v[120:123], v[56:59]
	ds_read_b64_tr_b16 v[124:125], v202 offset:224
	ds_read_b64_tr_b16 v[126:127], v202 offset:4832
	s_waitcnt lgkmcnt(6)
	v_mfma_f32_16x16x32_bf16 v[88:91], v[128:131], v[104:107], v[88:91]
	v_mfma_f32_16x16x32_bf16 v[56:59], v[128:131], v[116:119], v[56:59]
	ds_read_b64_tr_b16 v[128:129], v202 offset:9440
	ds_read_b64_tr_b16 v[130:131], v202 offset:14048
	s_waitcnt lgkmcnt(6)
	v_mfma_f32_16x16x32_bf16 v[88:91], v[132:135], v[100:103], v[88:91]
	v_mfma_f32_16x16x32_bf16 v[56:59], v[132:135], v[112:115], v[56:59]
	ds_read_b64_tr_b16 v[132:133], v202 offset:18656
	ds_read_b64_tr_b16 v[134:135], v202 offset:23264
	s_waitcnt lgkmcnt(6)
	v_mfma_f32_16x16x32_bf16 v[88:91], v[136:139], v[92:95], v[88:91]
	v_mfma_f32_16x16x32_bf16 v[56:59], v[136:139], v[84:87], v[56:59]
	ds_read_b64_tr_b16 v[136:137], v202 offset:27872
	ds_read_b64_tr_b16 v[138:139], v202 offset:32480
	s_waitcnt lgkmcnt(6)
	v_mfma_f32_16x16x32_bf16 v[96:99], v[124:127], v[108:111], v[96:99]
	v_mfma_f32_16x16x32_bf16 v[108:111], v[124:127], v[120:123], v[144:147]
	s_waitcnt lgkmcnt(4)
	v_mfma_f32_16x16x32_bf16 v[96:99], v[128:131], v[104:107], v[96:99]
	v_mfma_f32_16x16x32_bf16 v[104:107], v[128:131], v[116:119], v[108:111]
	s_waitcnt lgkmcnt(2)
	v_mfma_f32_16x16x32_bf16 v[96:99], v[132:135], v[100:103], v[96:99]
	v_mfma_f32_16x16x32_bf16 v[100:103], v[132:135], v[112:115], v[104:107]
	s_waitcnt lgkmcnt(0)
	v_mfma_f32_16x16x32_bf16 v[96:99], v[136:139], v[92:95], v[96:99]
	v_mfma_f32_16x16x32_bf16 v[84:87], v[136:139], v[84:87], v[100:103]
	s_cbranch_vccnz .LBB0_614
	v_mov_b32_e32 v209, v207
	v_mov_b32_e32 v208, v148
	s_cmp_eq_u32 s51, 0
	s_cbranch_scc0 .LBB0_605
	s_branch .LBB0_606
